# DeltaNet chunk: kend fragment reads of the state update hoisted next to the v-tile reads (on top of S4/S6 hoisting)
# speedup vs baseline: 1.0049x; 1.0021x over previous
.LBB0_541:
	s_or_b64 exec, exec, s[2:3]
	s_sub_i32 s14, s11, 32
	s_add_i32 s15, s25, 32
	v_lshlrev_b32_e32 v152, 5, v168
	s_and_b64 s[2:3], s[12:13], exec
	v_or_b32_e32 v153, v152, v165
	v_add_u32_e32 v154, 16, v170
	s_cselect_b32 s2, s14, s15
	v_mad_u64_u32 v[194:195], s[14:15], v153, s69, v[154:155]
	s_waitcnt lgkmcnt(0)
	s_barrier
	ds_read_b128 v[60:63], v172 offset:49664
	ds_read_b128 v[64:67], v172
	ds_read_b128 v[156:159], v194 offset:17408
	ds_read_b128 v[186:189], v194 offset:21760
	ds_read_b128 v[220:223], v172 offset:49728
	ds_read_b128 v[224:227], v172 offset:64
	ds_read_b128 v[228:231], v194 offset:17472
	ds_read_b128 v[232:235], v194 offset:21824
	ds_read_b128 v[236:239], v172 offset:49792
	ds_read_b128 v[240:243], v172 offset:128
	ds_read_b128 v[244:247], v194 offset:17536
	ds_read_b128 v[248:251], v194 offset:21888
	s_waitcnt lgkmcnt(9)
	v_mfma_f32_16x16x32_bf16 v[182:185], v[60:63], v[156:159], 0
	v_mfma_f32_16x16x32_bf16 v[156:159], v[64:67], v[156:159], 0
	v_mul_u32_u24_e32 v167, 0x104, v169
	v_lshl_add_u32 v168, v169, 1, s83
	v_lshl_add_u32 v155, v0, 1, 16
	v_lshlrev_b32_e32 v0, 1, v165
	v_cmp_gt_u32_e32 vcc, s61, v166
	s_waitcnt lgkmcnt(8)
	v_mfma_f32_16x16x32_bf16 v[60:63], v[60:63], v[186:189], 0
	v_mfma_f32_16x16x32_bf16 v[64:67], v[64:67], v[186:189], 0
	ds_read_b128 v[190:193], v172 offset:49856
	ds_read_b128 v[200:203], v172 offset:192
	ds_read_b128 v[186:189], v194 offset:17600
	v_lshl_or_b32 v109, v109, 5, v165
	s_add_i32 s2, s2, s96
	s_add_i32 s11, s11, 32
	s_sub_i32 s25, s25, 32
	s_cmp_eq_u32 s8, s10
	s_waitcnt lgkmcnt(7)
	v_mfma_f32_16x16x32_bf16 v[182:185], v[220:223], v[228:231], v[182:185]
	v_mfma_f32_16x16x32_bf16 v[156:159], v[224:227], v[228:231], v[156:159]
	v_mfma_f32_16x16x32_bf16 v[60:63], v[220:223], v[232:235], v[60:63]
	v_mfma_f32_16x16x32_bf16 v[64:67], v[224:227], v[232:235], v[64:67]
	ds_read_b128 v[220:223], v194 offset:21952
	v_lshlrev_b32_e32 v172, 2, v153
	v_add3_u32 v167, 16, v167, v172
	v_add_u32_e32 v167, 0xe400, v167
	v_mul_lo_u32 v153, v153, s82
	v_add_u32_e32 v181, v168, v153
	s_waitcnt lgkmcnt(4)
	v_mfma_f32_16x16x32_bf16 v[182:185], v[236:239], v[244:247], v[182:185]
	v_mfma_f32_16x16x32_bf16 v[156:159], v[240:243], v[244:247], v[156:159]
	v_mfma_f32_16x16x32_bf16 v[60:63], v[236:239], v[248:251], v[60:63]
	v_mfma_f32_16x16x32_bf16 v[64:67], v[240:243], v[248:251], v[64:67]
	s_waitcnt lgkmcnt(0)
	v_mfma_f32_16x16x32_bf16 v[182:185], v[190:193], v[186:189], v[182:185]
	v_mfma_f32_16x16x32_bf16 v[156:159], v[200:203], v[186:189], v[156:159]
	v_mfma_f32_16x16x32_bf16 v[60:63], v[190:193], v[220:223], v[60:63]
	v_mfma_f32_16x16x32_bf16 v[64:67], v[200:203], v[220:223], v[64:67]
	ds_read2_b32 v[186:187], v167 offset1:16
	s_waitcnt lgkmcnt(0)
	v_sub_f32_e32 v172, v186, v182
	ds_read2_b32 v[190:191], v167 offset0:65 offset1:81
	s_nop 2
	v_sub_f32_e32 v60, v187, v60
	v_add_u32_e32 v192, 0x500, v153
	v_cvt_pk_bf16_f32 v60, v60, s0
	v_add_u32_e32 v168, v168, v192
	ds_write_b16 v168, v60
	v_mul_u32_u24_e32 v60, 0x50, v169
	v_cvt_pk_bf16_f32 v172, v172, s0
	v_add3_u32 v155, v155, v0, v60
	s_waitcnt lgkmcnt(1)
	v_sub_f32_e32 v60, v190, v183
	v_add_u32_e32 v153, s83, v153
	v_lshlrev_b32_e32 v168, 1, v176
	ds_write_b16 v181, v172
	ds_write_b16 v155, v180 offset:45056
	v_cvt_pk_bf16_f32 v60, v60, s0
	v_add_u32_e32 v176, v153, v168
	ds_read_b128 v[180:183], v173 offset:384
	ds_read_b128 v[186:189], v173 offset:128
	ds_write_b16 v176, v60
	v_sub_f32_e32 v60, v191, v61
	v_add_u32_e32 v176, s83, v192
	v_cvt_pk_bf16_f32 v60, v60, s0
	v_add_u32_e32 v61, v176, v168
	ds_write_b16 v61, v60
	ds_write_b16 v155, v178 offset:45136
	ds_read2_b32 v[60:61], v167 offset0:130 offset1:146
	v_lshlrev_b32_e32 v168, 1, v175
	v_add_u32_e32 v175, v153, v168
	s_waitcnt lgkmcnt(4)
	v_pk_mul_f32 v[172:173], v[180:181], v[186:187]
	s_waitcnt lgkmcnt(0)
	v_sub_f32_e32 v60, v60, v184
	v_cvt_pk_bf16_f32 v60, v60, s0
	ds_write_b16 v175, v60
	v_sub_f32_e32 v60, v61, v62
	v_cvt_pk_bf16_f32 v60, v60, s0
	v_add_u32_e32 v61, v176, v168
	ds_write_b16 v61, v60
	ds_write_b16 v155, v179 offset:45216
	ds_read2_b32 v[60:61], v167 offset0:195 offset1:211
	v_lshlrev_b32_e32 v62, 1, v174
	v_add_u32_e32 v153, v153, v62
	v_pk_mul_f32 v[156:157], v[156:157], v[172:173]
	v_pk_mul_f32 v[64:65], v[64:65], v[172:173]
	s_waitcnt lgkmcnt(0)
	v_sub_f32_e32 v60, v60, v185
	v_cvt_pk_bf16_f32 v60, v60, s0
	ds_write_b16 v153, v60
	v_sub_f32_e32 v60, v61, v63
	v_cvt_pk_bf16_f32 v60, v60, s0
	v_add_u32_e32 v61, v176, v62
	ds_write_b16 v61, v60
	ds_write_b16 v155, v177 offset:45296
	v_mov_b32_e32 v60, s71
	s_waitcnt lgkmcnt(0)
	s_barrier
	ds_read_b32 v168, v60
	v_mad_u32_u24 v60, v171, s82, v154
	ds_read_b128 v[172:175], v60 offset:45056
	v_mul_u32_u24_e32 v60, 0x50, v165
	v_pk_mul_f32 v[178:179], v[182:183], v[188:189]
	v_add3_u32 v60, s83, v170, v60
	v_pk_mul_f32 v[158:159], v[158:159], v[178:179]
	v_pk_mul_f32 v[66:67], v[66:67], v[178:179]
	ds_read_b128 v[176:179], v60
	ds_read_b128 v[180:183], v60 offset:1280
	ds_read_b128 v[184:187], v60 offset:2560
	ds_read_b128 v[188:191], v60 offset:3840
	v_mad_u64_u32 v[232:233], s[14:15], v109, s82, v[154:155]
	ds_read_b128 v[220:223], v232 offset:34816
	ds_read_b128 v[224:227], v232 offset:36096
	s_waitcnt lgkmcnt(7)
	v_pk_mul_f32 v[18:19], v[18:19], v[168:169] op_sel_hi:[1,0]
	v_pk_mul_f32 v[16:17], v[16:17], v[168:169] op_sel_hi:[1,0]
	v_pk_mul_f32 v[14:15], v[14:15], v[168:169] op_sel_hi:[1,0]
	s_waitcnt lgkmcnt(3)
	v_cndmask_b32_e32 v63, v187, v179, vcc
	v_cndmask_b32_e32 v62, v186, v178, vcc
	v_cndmask_b32_e32 v61, v185, v177, vcc
	v_cndmask_b32_e32 v60, v184, v176, vcc
	v_pk_mul_f32 v[12:13], v[12:13], v[168:169] op_sel_hi:[1,0]
	v_pk_mul_f32 v[6:7], v[6:7], v[168:169] op_sel_hi:[1,0]
	v_mfma_f32_16x16x32_bf16 v[60:63], v[172:175], v[60:63], v[156:159]
	v_mul_f32_e64 v4, v4, v168
	v_mul_f32_e64 v5, v5, v168
	v_pk_mul_f32 v[10:11], v[10:11], v[168:169] op_sel_hi:[1,0]
	v_pk_mul_f32 v[8:9], v[8:9], v[168:169] op_sel_hi:[1,0]
	s_waitcnt lgkmcnt(2)
	v_cndmask_b32_e32 v159, v191, v183, vcc
	v_cndmask_b32_e32 v158, v190, v182, vcc
	v_cndmask_b32_e32 v157, v189, v181, vcc
	v_cndmask_b32_e32 v156, v188, v180, vcc
	v_pk_mul_f32 v[26:27], v[26:27], v[168:169] op_sel_hi:[1,0]
	v_pk_mul_f32 v[24:25], v[24:25], v[168:169] op_sel_hi:[1,0]
	v_mfma_f32_16x16x32_bf16 v[64:67], v[172:175], v[156:159], v[64:67]
	v_mad_u64_u32 v[158:159], s[14:15], v109, s82, v[154:155]
	s_nop 0
	s_waitcnt lgkmcnt(0)
	v_mfma_f32_16x16x32_bf16 v[16:19], v[220:223], v[176:179], v[16:19]
	v_mul_f32_e64 v22, v22, v168
	v_mul_f32_e64 v23, v23, v168
	v_pk_mul_f32 v[20:21], v[20:21], v[168:169] op_sel_hi:[1,0]
	v_pk_mul_f32 v[34:35], v[34:35], v[168:169] op_sel_hi:[1,0]
	v_mfma_f32_16x16x32_bf16 v[12:15], v[220:223], v[180:183], v[12:15]
	v_mul_f32_e64 v32, v32, v168
	v_mul_f32_e64 v33, v33, v168
	v_pk_mul_f32 v[30:31], v[30:31], v[168:169] op_sel_hi:[1,0]
	v_pk_mul_f32 v[28:29], v[28:29], v[168:169] op_sel_hi:[1,0]
	v_mfma_f32_16x16x32_bf16 v[4:7], v[220:223], v[184:187], v[4:7]
	v_mov_b32_e32 v109, s2
	v_ashrrev_i32_e32 v153, 31, v152
	v_lshlrev_b64 v[152:153], 1, v[152:153]
	v_mfma_f32_16x16x32_bf16 v[8:11], v[220:223], v[188:191], v[8:11]
	s_nop 0
	v_cvt_pk_bf16_f32 v60, v60, s0
	s_waitcnt lgkmcnt(0)
	v_mfma_f32_16x16x32_bf16 v[24:27], v[224:227], v[176:179], v[24:27]
	v_mfma_f32_16x16x32_bf16 v[20:23], v[224:227], v[180:183], v[20:23]
	v_mfma_f32_16x16x32_bf16 v[32:35], v[224:227], v[184:187], v[32:35]
	v_mfma_f32_16x16x32_bf16 v[28:31], v[224:227], v[188:191], v[28:31]
	v_mad_i32_i24 v154, v169, s97, v109
	v_ashrrev_i32_e32 v155, 31, v154
	v_lshlrev_b64 v[156:157], 12, v[154:155]
	v_lshl_add_u64 v[156:157], s[58:59], 0, v[156:157]
	v_lshl_add_u64 v[156:157], v[156:157], 0, v[0:1]
	v_lshl_add_u64 v[156:157], v[156:157], 0, v[152:153]
	v_add_u32_e32 v154, s97, v154
	global_store_short v[156:157], v60, off offset:2048
	v_cvt_pk_bf16_f32 v60, v64, s0
	v_ashrrev_i32_e32 v155, 31, v154
	global_store_short v[156:157], v60, off offset:2080
	v_lshlrev_b64 v[156:157], 12, v[154:155]
	v_lshl_add_u64 v[156:157], s[58:59], 0, v[156:157]
	v_lshl_add_u64 v[156:157], v[156:157], 0, v[0:1]
	v_cvt_pk_bf16_f32 v64, v61, s0
	v_lshl_add_u64 v[60:61], v[156:157], 0, v[152:153]
	global_store_short v[60:61], v64, off offset:2048
	v_cvt_pk_bf16_f32 v64, v65, s0
	global_store_short v[60:61], v64, off offset:2080
	v_add_u32_e32 v60, s97, v154
	v_ashrrev_i32_e32 v61, 31, v60
	v_lshlrev_b64 v[64:65], 12, v[60:61]
	v_lshl_add_u64 v[64:65], s[58:59], 0, v[64:65]
	v_lshl_add_u64 v[64:65], v[64:65], 0, v[0:1]
	v_cvt_pk_bf16_f32 v61, v62, s0
	v_lshl_add_u64 v[64:65], v[64:65], 0, v[152:153]
	global_store_short v[64:65], v61, off offset:2048
	v_cvt_pk_bf16_f32 v61, v66, s0
	v_add_u32_e32 v60, s97, v60
	global_store_short v[64:65], v61, off offset:2080
	v_ashrrev_i32_e32 v61, 31, v60
	v_lshlrev_b64 v[60:61], 12, v[60:61]
	v_lshl_add_u64 v[60:61], s[58:59], 0, v[60:61]
	v_lshl_add_u64 v[60:61], v[60:61], 0, v[0:1]
	v_cvt_pk_bf16_f32 v0, v63, s0
	v_lshl_add_u64 v[60:61], v[60:61], 0, v[152:153]
	global_store_short v[60:61], v0, off offset:2048
	v_cvt_pk_bf16_f32 v0, v67, s0
	global_store_short v[60:61], v0, off offset:2080
	s_cbranch_scc1 .LBB0_606
